# isel: next item's head weights / query fragments / first key fragments prefetched during the top-k stage into registers it never touches; weights unpacked at the item tail; prologue skips loads when p
# speedup vs baseline: 1.0038x; 1.0033x over previous
.LBB0_294:
	s_cmp_le_i32 s76, s29
	s_cselect_b64 s[0:1], -1, 0
	s_and_b64 s[0:1], s[0:1], s[6:7]
	s_andn2_b64 vcc, exec, s[0:1]
	s_cbranch_vccnz .LBB0_706
	v_readlane_b32 s0, v238, 16
	v_readlane_b32 s1, v238, 17
	s_andn2_b64 vcc, exec, s[0:1]
	s_cbranch_vccnz .LBB0_652
	v_readlane_b32 s2, v236, 1
	v_readlane_b32 s4, v237, 25
	s_mul_i32 s1, s2, 0x3000
	v_readlane_b32 s6, v237, 27
	s_mul_hi_u32 s0, s2, 0x3000
	v_readlane_b32 s5, v237, 26
	v_readlane_b32 s7, v237, 28
	s_add_u32 s4, s6, s1
	s_addc_u32 s5, s7, s0
	v_writelane_b32 v236, s4, 5
	s_lshl_b32 s0, s2, 12
	s_mov_b32 s44, s68
	v_writelane_b32 v236, s5, 6
	s_mov_b32 s101, -1
	s_mov_b32 s45, s68
	v_writelane_b32 v236, s0, 7
	s_branch .LBB0_299
.LBB0_297:
	s_add_i32 s98, s45, s69
	s_cmp_lg_u32 s101, s98
	s_cbranch_scc1 .Lipf_tail
	s_waitcnt vmcnt(0)
	v_and_b32_e32 v5, 0xffff0000, v178
	v_lshlrev_b32_e32 v4, 16, v178
	v_mul_f32_e32 v67, 0x3d000000, v5
	v_mul_f32_e32 v66, 0x3d000000, v4
	v_and_b32_e32 v5, 0xffff0000, v179
	v_lshlrev_b32_e32 v4, 16, v179
	v_mul_f32_e32 v69, 0x3d000000, v5
	v_mul_f32_e32 v68, 0x3d000000, v4
	v_and_b32_e32 v5, 0xffff0000, v180
	v_lshlrev_b32_e32 v4, 16, v180
	v_mul_f32_e32 v71, 0x3d000000, v5
	v_mul_f32_e32 v70, 0x3d000000, v4
	v_and_b32_e32 v5, 0xffff0000, v181
	v_lshlrev_b32_e32 v4, 16, v181
	v_mul_f32_e32 v73, 0x3d000000, v5
	v_mul_f32_e32 v72, 0x3d000000, v4
	v_and_b32_e32 v5, 0xffff0000, v182
	v_lshlrev_b32_e32 v4, 16, v182
	v_mul_f32_e32 v75, 0x3d000000, v5
	v_mul_f32_e32 v74, 0x3d000000, v4
	v_and_b32_e32 v5, 0xffff0000, v183
	v_lshlrev_b32_e32 v4, 16, v183
	v_mul_f32_e32 v77, 0x3d000000, v5
	v_mul_f32_e32 v76, 0x3d000000, v4
	v_and_b32_e32 v5, 0xffff0000, v184
	v_lshlrev_b32_e32 v4, 16, v184
	v_mul_f32_e32 v79, 0x3d000000, v5
	v_mul_f32_e32 v78, 0x3d000000, v4
	v_and_b32_e32 v5, 0xffff0000, v185
	v_lshlrev_b32_e32 v4, 16, v185
	v_mul_f32_e32 v81, 0x3d000000, v5
	v_mul_f32_e32 v80, 0x3d000000, v4
	v_and_b32_e32 v5, 0xffff0000, v186
	v_lshlrev_b32_e32 v4, 16, v186
	v_mul_f32_e32 v83, 0x3d000000, v5
	v_mul_f32_e32 v82, 0x3d000000, v4
	v_and_b32_e32 v5, 0xffff0000, v187
	v_lshlrev_b32_e32 v4, 16, v187
	v_mul_f32_e32 v165, 0x3d000000, v5
	v_mul_f32_e32 v164, 0x3d000000, v4
	v_and_b32_e32 v5, 0xffff0000, v188
	v_lshlrev_b32_e32 v4, 16, v188
	v_mul_f32_e32 v167, 0x3d000000, v5
	v_mul_f32_e32 v166, 0x3d000000, v4
	v_and_b32_e32 v5, 0xffff0000, v189
	v_lshlrev_b32_e32 v4, 16, v189
	v_mul_f32_e32 v169, 0x3d000000, v5
	v_mul_f32_e32 v168, 0x3d000000, v4
	v_and_b32_e32 v5, 0xffff0000, v190
	v_lshlrev_b32_e32 v4, 16, v190
	v_mul_f32_e32 v171, 0x3d000000, v5
	v_mul_f32_e32 v170, 0x3d000000, v4
	v_and_b32_e32 v5, 0xffff0000, v191
	v_lshlrev_b32_e32 v4, 16, v191
	v_mul_f32_e32 v173, 0x3d000000, v5
	v_mul_f32_e32 v172, 0x3d000000, v4
	v_and_b32_e32 v5, 0xffff0000, v192
	v_lshlrev_b32_e32 v4, 16, v192
	v_mul_f32_e32 v175, 0x3d000000, v5
	v_mul_f32_e32 v174, 0x3d000000, v4
	v_and_b32_e32 v5, 0xffff0000, v193
	v_lshlrev_b32_e32 v4, 16, v193
	v_mul_f32_e32 v177, 0x3d000000, v5
	v_mul_f32_e32 v176, 0x3d000000, v4
	v_and_b32_e32 v5, 0xffff0000, v194
	v_lshlrev_b32_e32 v4, 16, v194
	v_mul_f32_e32 v179, 0x3d000000, v5
	v_mul_f32_e32 v178, 0x3d000000, v4
	v_and_b32_e32 v5, 0xffff0000, v195
	v_lshlrev_b32_e32 v4, 16, v195
	v_mul_f32_e32 v181, 0x3d000000, v5
	v_mul_f32_e32 v180, 0x3d000000, v4
	v_and_b32_e32 v5, 0xffff0000, v196
	v_lshlrev_b32_e32 v4, 16, v196
	v_mul_f32_e32 v183, 0x3d000000, v5
	v_mul_f32_e32 v182, 0x3d000000, v4
	v_and_b32_e32 v5, 0xffff0000, v197
	v_lshlrev_b32_e32 v4, 16, v197
	v_mul_f32_e32 v185, 0x3d000000, v5
	v_mul_f32_e32 v184, 0x3d000000, v4
	v_and_b32_e32 v5, 0xffff0000, v198
	v_lshlrev_b32_e32 v4, 16, v198
	v_mul_f32_e32 v187, 0x3d000000, v5
	v_mul_f32_e32 v186, 0x3d000000, v4
	v_and_b32_e32 v5, 0xffff0000, v199
	v_lshlrev_b32_e32 v4, 16, v199
	v_mul_f32_e32 v189, 0x3d000000, v5
	v_mul_f32_e32 v188, 0x3d000000, v4
	v_and_b32_e32 v5, 0xffff0000, v200
	v_lshlrev_b32_e32 v4, 16, v200
	v_mul_f32_e32 v191, 0x3d000000, v5
	v_mul_f32_e32 v190, 0x3d000000, v4
	v_and_b32_e32 v5, 0xffff0000, v201
	v_lshlrev_b32_e32 v4, 16, v201
	v_mul_f32_e32 v193, 0x3d000000, v5
	v_mul_f32_e32 v192, 0x3d000000, v4
	v_and_b32_e32 v5, 0xffff0000, v202
	v_lshlrev_b32_e32 v4, 16, v202
	v_mul_f32_e32 v195, 0x3d000000, v5
	v_mul_f32_e32 v194, 0x3d000000, v4
	v_and_b32_e32 v5, 0xffff0000, v203
	v_lshlrev_b32_e32 v4, 16, v203
	v_mul_f32_e32 v197, 0x3d000000, v5
	v_mul_f32_e32 v196, 0x3d000000, v4
	v_and_b32_e32 v5, 0xffff0000, v204
	v_lshlrev_b32_e32 v4, 16, v204
	v_mul_f32_e32 v199, 0x3d000000, v5
	v_mul_f32_e32 v198, 0x3d000000, v4
	v_and_b32_e32 v5, 0xffff0000, v205
	v_lshlrev_b32_e32 v4, 16, v205
	v_mul_f32_e32 v201, 0x3d000000, v5
	v_mul_f32_e32 v200, 0x3d000000, v4
	v_and_b32_e32 v5, 0xffff0000, v206
	v_lshlrev_b32_e32 v4, 16, v206
	v_mul_f32_e32 v203, 0x3d000000, v5
	v_mul_f32_e32 v202, 0x3d000000, v4
	v_and_b32_e32 v5, 0xffff0000, v207
	v_lshlrev_b32_e32 v4, 16, v207
	v_mul_f32_e32 v205, 0x3d000000, v5
	v_mul_f32_e32 v204, 0x3d000000, v4
	v_and_b32_e32 v5, 0xffff0000, v208
	v_lshlrev_b32_e32 v4, 16, v208
	v_mul_f32_e32 v207, 0x3d000000, v5
	v_mul_f32_e32 v206, 0x3d000000, v4
	v_and_b32_e32 v5, 0xffff0000, v209
	v_lshlrev_b32_e32 v4, 16, v209
	v_mul_f32_e32 v209, 0x3d000000, v5
	v_mul_f32_e32 v208, 0x3d000000, v4

.LBB0_330:
	s_and_b32 s2, s45, 0xff
	s_ashr_i32 s1, s45, 9
	s_and_b32 s0, s45, 0x100
	s_xor_b32 s3, s2, 0x1ff
	s_cmp_eq_u32 s0, 0
	v_mov_b32_e32 v13, v212
	s_cselect_b32 s2, s2, s3
	s_lshl_b32 s29, s2, 3
	v_readfirstlane_b32 s0, v13
	s_lshl_b32 s49, s1, 12
	s_lshr_b32 s34, s2, 2
	s_ashr_i32 s0, s0, 6
	s_cmp_gt_i32 s0, s34
	v_and_b32_e32 v221, 63, v13
	s_cbranch_scc1 .LBB0_335
	s_or_b32 s6, s29, s49
	s_lshl_b32 s2, s2, 11
	s_lshl_b32 s4, s6, 1
	s_and_b32 s35, s2, 0xf000
	s_or_b32 s2, s4, 1
	s_ashr_i32 s3, s2, 31
	s_lshl_b64 s[38:39], s[2:3], 10
	s_or_b32 s2, s4, 2
	s_ashr_i32 s3, s2, 31
	s_lshl_b64 s[40:41], s[2:3], 10
	s_or_b32 s2, s4, 3
	s_ashr_i32 s3, s2, 31
	s_lshl_b64 s[42:43], s[2:3], 10
	s_ashr_i32 s2, s6, 8
	s_mulk_i32 s2, 0x49
	s_ashr_i32 s3, s2, 31
	s_lshl_b64 s[30:31], s[2:3], 17
	s_or_b32 s2, s4, 4
	s_ashr_i32 s3, s2, 31
	s_lshl_b64 s[20:21], s[2:3], 10
	s_or_b32 s2, s4, 5
	s_ashr_i32 s3, s2, 31
	s_lshl_b64 s[22:23], s[2:3], 10
	s_or_b32 s2, s4, 6
	s_ashr_i32 s3, s2, 31
	s_lshl_b64 s[24:25], s[2:3], 10
	s_or_b32 s2, s4, 7
	s_ashr_i32 s3, s2, 31
	s_lshl_b64 s[26:27], s[2:3], 10
	s_or_b32 s2, s4, 8
	s_ashr_i32 s3, s2, 31
	s_lshl_b64 s[12:13], s[2:3], 10
	s_or_b32 s2, s4, 9
	s_ashr_i32 s3, s2, 31
	s_lshl_b64 s[14:15], s[2:3], 10
	s_or_b32 s2, s4, 10
	s_ashr_i32 s5, s4, 31
	s_ashr_i32 s3, s2, 31
	s_lshl_b64 s[36:37], s[4:5], 10
	s_lshl_b64 s[16:17], s[2:3], 10
	s_or_b32 s2, s4, 11
	s_ashr_i32 s3, s2, 31
	s_lshl_b64 s[18:19], s[2:3], 10
	s_or_b32 s2, s4, 12
	s_or_b32 s6, s4, 13
	s_or_b32 s8, s4, 14
	s_or_b32 s4, s4, 15
	s_ashr_i32 s5, s4, 31
	s_lshl_b64 s[10:11], s[4:5], 10
	s_lshl_b32 s4, s1, 7
	s_ashr_i32 s3, s2, 31
	s_ashr_i32 s7, s6, 31
	s_ashr_i32 s9, s8, 31
	s_ashr_i32 s5, s4, 31
	s_lshl_b64 s[2:3], s[2:3], 10
	s_lshl_b64 s[6:7], s[6:7], 10
	s_lshl_b64 s[8:9], s[8:9], 10
	s_lshl_b64 s[4:5], s[4:5], 12
	v_readlane_b32 s36, v237, 5
	v_readlane_b32 s37, v237, 6
	s_add_u32 s30, s36, s30
	s_addc_u32 s31, s37, s31
	s_mov_b32 s1, 0x1bb00000
	s_mov_b64 s[30:31], 0x1bb00800
	s_mov_b32 s30, 0x3d000000
	v_readlane_b32 s36, v237, 46
	s_movk_i32 s41, 0x3fff
	s_mov_b32 s40, 0x800000
	s_movk_i32 s39, 0x1e0
	v_readlane_b32 s38, v237, 45
	v_readlane_b32 s37, v237, 47
	s_mov_b64 s[20:21], 0x1bb00880
	s_mov_b64 s[12:13], 0x1bb00900
	s_mov_b64 s[2:3], 0x1bb00980
	v_readlane_b32 s2, v239, 12
	v_readlane_b32 s3, v239, 13
	s_add_u32 s2, s2, s4
	s_addc_u32 s3, s3, s5
	s_ashr_i32 s1, s0, 31
	s_lshl_b64 s[2:3], s[0:1], 12
	s_lshl_b32 s1, s0, 7
	s_add_i32 s1, 0, 0x10000
	s_add_u32 s1, s2, s4
	s_addc_u32 s3, s3, s5
	v_readlane_b32 s2, v237, 3
	s_add_u32 s2, s2, s1
	v_readlane_b32 s1, v237, 4
	s_addc_u32 s3, s1, s3
	s_mov_b32 s1, s0
	v_lshlrev_b32_e32 v0, 4, v221
	v_lshrrev_b32_e32 v12, 5, v221
	v_and_b32_e32 v4, 31, v13
	s_or_b32 s2, s29, s49
	v_readlane_b32 s4, v237, 5
	v_readlane_b32 s5, v237, 6
	s_lshr_b32 s3, s2, 8
	s_mulk_i32 s3, 0x49
	s_lshl_b32 s3, s3, 17
	s_add_u32 s3, s3, 0x1bb00000
	s_add_u32 s4, s4, s3
	s_addc_u32 s5, s5, 0
	s_lshl_b32 s3, s29, 8
	s_and_b32 s3, s3, 0xf000
	v_or_b32_e32 v222, s29, v12
	v_lshlrev_b32_e32 v2, 5, v222
	v_and_b32_e32 v2, 0x120, v2
	v_or_b32_e32 v2, s3, v2
	v_lshlrev_b32_e32 v2, 1, v2
	v_mov_b32_e32 v3, v1
	v_lshl_add_u64 v[6:7], s[4:5], 0, v[2:3]
	s_cmp_eq_u32 s101, s45
	s_cbranch_scc1 .Lipf_skip0
	global_load_dwordx4 v[178:181], v[6:7], off offset:2048
	global_load_dwordx4 v[182:185], v[6:7], off offset:2064
	global_load_dwordx4 v[186:189], v[6:7], off offset:2176
	global_load_dwordx4 v[190:193], v[6:7], off offset:2192
	global_load_dwordx4 v[194:197], v[6:7], off offset:2304
	global_load_dwordx4 v[198:201], v[6:7], off offset:2320
	global_load_dwordx4 v[202:205], v[6:7], off offset:2432
	global_load_dwordx4 v[206:209], v[6:7], off offset:2448
.Lipf_skip0:
	s_lshl_b32 s3, s2, 11
	s_add_u32 s4, s82, s3
	s_addc_u32 s5, s83, 0
	s_add_u32 s4, s4, 0x1000
	s_addc_u32 s5, s5, 0
	v_lshl_add_u64 v[8:9], s[4:5], 0, v[0:1]
	s_add_u32 s4, s4, 0x2000
	s_addc_u32 s5, s5, 0
	v_lshl_add_u64 v[10:11], s[4:5], 0, v[0:1]
	s_cmp_eq_u32 s101, s45
	s_cbranch_scc1 .Lipf_skip1
	global_load_dwordx4 v[84:87], v[8:9], off offset:-4096
	global_load_dwordx4 v[88:91], v[8:9], off offset:-3072
	global_load_dwordx4 v[92:95], v[8:9], off offset:-2048
	global_load_dwordx4 v[96:99], v[8:9], off offset:-1024
	global_load_dwordx4 v[100:103], v[8:9], off
	global_load_dwordx4 v[104:107], v[8:9], off offset:1024
	global_load_dwordx4 v[108:111], v[8:9], off offset:2048
	global_load_dwordx4 v[112:115], v[8:9], off offset:3072
	global_load_dwordx4 v[116:119], v[10:11], off offset:-4096
	global_load_dwordx4 v[120:123], v[10:11], off offset:-3072
	global_load_dwordx4 v[124:127], v[10:11], off offset:-2048
	global_load_dwordx4 v[128:131], v[10:11], off offset:-1024
	global_load_dwordx4 v[132:135], v[10:11], off
	global_load_dwordx4 v[136:139], v[10:11], off offset:1024
	global_load_dwordx4 v[140:143], v[10:11], off offset:2048
	global_load_dwordx4 v[144:147], v[10:11], off offset:3072
.Lipf_skip1:
	v_readlane_b32 s4, v239, 12
	v_readlane_b32 s5, v239, 13
	s_lshl_b32 s3, s49, 7
	s_lshl_b32 s2, s0, 12
	s_add_u32 s3, s3, s2
	s_add_u32 s4, s4, s3
	s_addc_u32 s5, s5, 0
	v_lshl_add_u64 v[2:3], s[4:5], 0, v[0:1]
	s_cmp_eq_u32 s101, s45
	s_cbranch_scc1 .Lipf_skip2
	global_load_dwordx4 v[148:151], v[2:3], off
	global_load_dwordx4 v[152:155], v[2:3], off offset:1024
	global_load_dwordx4 v[156:159], v[2:3], off offset:2048
	global_load_dwordx4 v[160:163], v[2:3], off offset:3072
.Lipf_skip2:
	s_add_u32 s4, s4, 0x8800
	s_addc_u32 s5, s5, 0
	v_lshl_add_u64 v[210:211], s[4:5], 0, v[0:1]
	v_or_b32_e32 v223, 2, v222
	v_or_b32_e32 v224, 4, v222
	v_or_b32_e32 v225, 6, v222
	s_lshl_b32 s2, s0, 7
	v_lshlrev_b32_e32 v2, 14, v12
	v_lshl_or_b32 v2, v4, 2, v2
	v_add_u32_e32 v2, s2, v2
	v_add_u32_e32 v227, 0x10000, v2
	v_lshl_or_b32 v226, s0, 5, v4
	s_cmp_eq_u32 s101, s45
	s_cbranch_scc1 .Lipf_skipu
	s_waitcnt vmcnt(20)
	v_and_b32_e32 v3, 0xffff0000, v178
	v_lshlrev_b32_e32 v2, 16, v178
	v_mul_f32_e32 v67, s30, v3
	v_mul_f32_e32 v66, s30, v2
	v_and_b32_e32 v3, 0xffff0000, v179
	v_lshlrev_b32_e32 v2, 16, v179
	v_mul_f32_e32 v69, s30, v3
	v_mul_f32_e32 v68, s30, v2
	v_and_b32_e32 v3, 0xffff0000, v180
	v_lshlrev_b32_e32 v2, 16, v180
	v_mul_f32_e32 v71, s30, v3
	v_mul_f32_e32 v70, s30, v2
	v_and_b32_e32 v3, 0xffff0000, v181
	v_lshlrev_b32_e32 v2, 16, v181
	v_mul_f32_e32 v73, s30, v3
	v_mul_f32_e32 v72, s30, v2
	v_and_b32_e32 v3, 0xffff0000, v182
	v_lshlrev_b32_e32 v2, 16, v182
	v_mul_f32_e32 v75, s30, v3
	v_mul_f32_e32 v74, s30, v2
	v_and_b32_e32 v3, 0xffff0000, v183
	v_lshlrev_b32_e32 v2, 16, v183
	v_mul_f32_e32 v77, s30, v3
	v_mul_f32_e32 v76, s30, v2
	v_and_b32_e32 v3, 0xffff0000, v184
	v_lshlrev_b32_e32 v2, 16, v184
	v_mul_f32_e32 v79, s30, v3
	v_mul_f32_e32 v78, s30, v2
	v_and_b32_e32 v3, 0xffff0000, v185
	v_lshlrev_b32_e32 v2, 16, v185
	v_mul_f32_e32 v81, s30, v3
	v_mul_f32_e32 v80, s30, v2
	v_and_b32_e32 v3, 0xffff0000, v186
	v_lshlrev_b32_e32 v2, 16, v186
	v_mul_f32_e32 v83, s30, v3
	v_mul_f32_e32 v82, s30, v2
	v_and_b32_e32 v3, 0xffff0000, v187
	v_lshlrev_b32_e32 v2, 16, v187
	v_mul_f32_e32 v165, s30, v3
	v_mul_f32_e32 v164, s30, v2
	v_and_b32_e32 v3, 0xffff0000, v188
	v_lshlrev_b32_e32 v2, 16, v188
	v_mul_f32_e32 v167, s30, v3
	v_mul_f32_e32 v166, s30, v2
	v_and_b32_e32 v3, 0xffff0000, v189
	v_lshlrev_b32_e32 v2, 16, v189
	v_mul_f32_e32 v169, s30, v3
	v_mul_f32_e32 v168, s30, v2
	v_and_b32_e32 v3, 0xffff0000, v190
	v_lshlrev_b32_e32 v2, 16, v190
	v_mul_f32_e32 v171, s30, v3
	v_mul_f32_e32 v170, s30, v2
	v_and_b32_e32 v3, 0xffff0000, v191
	v_lshlrev_b32_e32 v2, 16, v191
	v_mul_f32_e32 v173, s30, v3
	v_mul_f32_e32 v172, s30, v2
	v_and_b32_e32 v3, 0xffff0000, v192
	v_lshlrev_b32_e32 v2, 16, v192
	v_mul_f32_e32 v175, s30, v3
	v_mul_f32_e32 v174, s30, v2
	v_and_b32_e32 v3, 0xffff0000, v193
	v_lshlrev_b32_e32 v2, 16, v193
	v_mul_f32_e32 v177, s30, v3
	v_mul_f32_e32 v176, s30, v2
	v_and_b32_e32 v3, 0xffff0000, v194
	v_lshlrev_b32_e32 v2, 16, v194
	v_mul_f32_e32 v179, s30, v3
	v_mul_f32_e32 v178, s30, v2
	v_and_b32_e32 v3, 0xffff0000, v195
	v_lshlrev_b32_e32 v2, 16, v195
	v_mul_f32_e32 v181, s30, v3
	v_mul_f32_e32 v180, s30, v2
	v_and_b32_e32 v3, 0xffff0000, v196
	v_lshlrev_b32_e32 v2, 16, v196
	v_mul_f32_e32 v183, s30, v3
	v_mul_f32_e32 v182, s30, v2
	v_and_b32_e32 v3, 0xffff0000, v197
	v_lshlrev_b32_e32 v2, 16, v197
	v_mul_f32_e32 v185, s30, v3
	v_mul_f32_e32 v184, s30, v2
	v_and_b32_e32 v3, 0xffff0000, v198
	v_lshlrev_b32_e32 v2, 16, v198
	v_mul_f32_e32 v187, s30, v3
	v_mul_f32_e32 v186, s30, v2
	v_and_b32_e32 v3, 0xffff0000, v199
	v_lshlrev_b32_e32 v2, 16, v199
	v_mul_f32_e32 v189, s30, v3
	v_mul_f32_e32 v188, s30, v2
	v_and_b32_e32 v3, 0xffff0000, v200
	v_lshlrev_b32_e32 v2, 16, v200
	v_mul_f32_e32 v191, s30, v3
	v_mul_f32_e32 v190, s30, v2
	v_and_b32_e32 v3, 0xffff0000, v201
	v_lshlrev_b32_e32 v2, 16, v201
	v_mul_f32_e32 v193, s30, v3
	v_mul_f32_e32 v192, s30, v2
	v_and_b32_e32 v3, 0xffff0000, v202
	v_lshlrev_b32_e32 v2, 16, v202
	v_mul_f32_e32 v195, s30, v3
	v_mul_f32_e32 v194, s30, v2
	v_and_b32_e32 v3, 0xffff0000, v203
	v_lshlrev_b32_e32 v2, 16, v203
	v_mul_f32_e32 v197, s30, v3
	v_mul_f32_e32 v196, s30, v2
	v_and_b32_e32 v3, 0xffff0000, v204
	v_lshlrev_b32_e32 v2, 16, v204
	v_mul_f32_e32 v199, s30, v3
	v_mul_f32_e32 v198, s30, v2
	v_and_b32_e32 v3, 0xffff0000, v205
	v_lshlrev_b32_e32 v2, 16, v205
	v_mul_f32_e32 v201, s30, v3
	v_mul_f32_e32 v200, s30, v2
	v_and_b32_e32 v3, 0xffff0000, v206
	v_lshlrev_b32_e32 v2, 16, v206
	v_mul_f32_e32 v203, s30, v3
	v_mul_f32_e32 v202, s30, v2
	v_and_b32_e32 v3, 0xffff0000, v207
	v_lshlrev_b32_e32 v2, 16, v207
	v_mul_f32_e32 v205, s30, v3
	v_mul_f32_e32 v204, s30, v2
	v_and_b32_e32 v3, 0xffff0000, v208
	v_lshlrev_b32_e32 v2, 16, v208
	v_mul_f32_e32 v207, s30, v3
	v_mul_f32_e32 v206, s30, v2
	v_and_b32_e32 v3, 0xffff0000, v209
	v_lshlrev_b32_e32 v2, 16, v209
	v_mul_f32_e32 v209, s30, v3
	v_mul_f32_e32 v208, s30, v2
.Lipf_skipu:
	s_branch .LBB0_333
.LBB0_332:
	s_nop 7
	v_max_f32_e32 v50, 0, v50
	v_max_f32_e32 v34, 0, v34
	v_max_f32_e32 v18, 0, v18
	v_max_f32_e32 v2, 0, v2
	v_mul_f32_e32 v228, v66, v50
	v_mul_f32_e32 v229, v82, v34
	v_mul_f32_e32 v230, v178, v18
	v_mul_f32_e32 v231, v194, v2
	v_max_f32_e32 v51, 0, v51
	v_max_f32_e32 v35, 0, v35
	v_max_f32_e32 v19, 0, v19
	v_max_f32_e32 v3, 0, v3
	v_fmac_f32_e32 v228, v67, v51
	v_fmac_f32_e32 v229, v83, v35
	v_fmac_f32_e32 v230, v179, v19
	v_fmac_f32_e32 v231, v195, v3
	v_max_f32_e32 v52, 0, v52
	v_max_f32_e32 v36, 0, v36
	v_max_f32_e32 v20, 0, v20
	v_max_f32_e32 v4, 0, v4
	v_fmac_f32_e32 v228, v68, v52
	v_fmac_f32_e32 v229, v164, v36
	v_fmac_f32_e32 v230, v180, v20
	v_fmac_f32_e32 v231, v196, v4
	v_max_f32_e32 v53, 0, v53
	v_max_f32_e32 v37, 0, v37
	v_max_f32_e32 v21, 0, v21
	v_max_f32_e32 v5, 0, v5
	v_fmac_f32_e32 v228, v69, v53
	v_fmac_f32_e32 v229, v165, v37
	v_fmac_f32_e32 v230, v181, v21
	v_fmac_f32_e32 v231, v197, v5
	v_max_f32_e32 v54, 0, v54
	v_max_f32_e32 v38, 0, v38
	v_max_f32_e32 v22, 0, v22
	v_max_f32_e32 v6, 0, v6
	v_fmac_f32_e32 v228, v70, v54
	v_fmac_f32_e32 v229, v166, v38
	v_fmac_f32_e32 v230, v182, v22
	v_fmac_f32_e32 v231, v198, v6
	v_max_f32_e32 v55, 0, v55
	v_max_f32_e32 v39, 0, v39
	v_max_f32_e32 v23, 0, v23
	v_max_f32_e32 v7, 0, v7
	v_fmac_f32_e32 v228, v71, v55
	v_fmac_f32_e32 v229, v167, v39
	v_fmac_f32_e32 v230, v183, v23
	v_fmac_f32_e32 v231, v199, v7
	v_max_f32_e32 v56, 0, v56
	v_max_f32_e32 v40, 0, v40
	v_max_f32_e32 v24, 0, v24
	v_max_f32_e32 v8, 0, v8
	v_fmac_f32_e32 v228, v72, v56
	v_fmac_f32_e32 v229, v168, v40
	v_fmac_f32_e32 v230, v184, v24
	v_fmac_f32_e32 v231, v200, v8
	v_max_f32_e32 v57, 0, v57
	v_max_f32_e32 v41, 0, v41
	v_max_f32_e32 v25, 0, v25
	v_max_f32_e32 v9, 0, v9
	v_fmac_f32_e32 v228, v73, v57
	v_fmac_f32_e32 v229, v169, v41
	v_fmac_f32_e32 v230, v185, v25
	v_fmac_f32_e32 v231, v201, v9
	v_max_f32_e32 v58, 0, v58
	v_max_f32_e32 v42, 0, v42
	v_max_f32_e32 v26, 0, v26
	v_max_f32_e32 v10, 0, v10
	v_fmac_f32_e32 v228, v74, v58
	v_fmac_f32_e32 v229, v170, v42
	v_fmac_f32_e32 v230, v186, v26
	v_fmac_f32_e32 v231, v202, v10
	v_max_f32_e32 v59, 0, v59
	v_max_f32_e32 v43, 0, v43
	v_max_f32_e32 v27, 0, v27
	v_max_f32_e32 v11, 0, v11
	v_fmac_f32_e32 v228, v75, v59
	v_fmac_f32_e32 v229, v171, v43
	v_fmac_f32_e32 v230, v187, v27
	v_fmac_f32_e32 v231, v203, v11
	v_max_f32_e32 v60, 0, v60
	v_max_f32_e32 v44, 0, v44
	v_max_f32_e32 v28, 0, v28
	v_max_f32_e32 v12, 0, v12
	v_fmac_f32_e32 v228, v76, v60
	v_fmac_f32_e32 v229, v172, v44
	v_fmac_f32_e32 v230, v188, v28
	v_fmac_f32_e32 v231, v204, v12
	v_max_f32_e32 v61, 0, v61
	v_max_f32_e32 v45, 0, v45
	v_max_f32_e32 v29, 0, v29
	v_max_f32_e32 v13, 0, v13
	v_fmac_f32_e32 v228, v77, v61
	v_fmac_f32_e32 v229, v173, v45
	v_fmac_f32_e32 v230, v189, v29
	v_fmac_f32_e32 v231, v205, v13
	v_max_f32_e32 v62, 0, v62
	v_max_f32_e32 v46, 0, v46
	v_max_f32_e32 v30, 0, v30
	v_max_f32_e32 v14, 0, v14
	v_fmac_f32_e32 v228, v78, v62
	v_fmac_f32_e32 v229, v174, v46
	v_fmac_f32_e32 v230, v190, v30
	v_fmac_f32_e32 v231, v206, v14
	v_max_f32_e32 v63, 0, v63
	v_max_f32_e32 v47, 0, v47
	v_max_f32_e32 v31, 0, v31
	v_max_f32_e32 v15, 0, v15
	v_fmac_f32_e32 v228, v79, v63
	v_fmac_f32_e32 v229, v175, v47
	v_fmac_f32_e32 v230, v191, v31
	v_fmac_f32_e32 v231, v207, v15
	v_max_f32_e32 v64, 0, v64
	v_max_f32_e32 v48, 0, v48
	v_max_f32_e32 v32, 0, v32
	v_max_f32_e32 v16, 0, v16
	v_fmac_f32_e32 v228, v80, v64
	v_fmac_f32_e32 v229, v176, v48
	v_fmac_f32_e32 v230, v192, v32
	v_fmac_f32_e32 v231, v208, v16
	v_max_f32_e32 v65, 0, v65
	v_max_f32_e32 v49, 0, v49
	v_max_f32_e32 v33, 0, v33
	v_max_f32_e32 v17, 0, v17
	v_fmac_f32_e32 v228, v81, v65
	v_fmac_f32_e32 v229, v177, v49
	v_fmac_f32_e32 v230, v193, v33
	v_fmac_f32_e32 v231, v209, v17
	v_ashrrev_i32_e32 v50, 31, v228
	v_ashrrev_i32_e32 v51, 31, v229
	v_ashrrev_i32_e32 v52, 31, v230
	v_ashrrev_i32_e32 v53, 31, v231
	v_cmp_le_i32_e32 vcc, v226, v222
	v_or_b32_e32 v50, v217, v50
	v_or_b32_e32 v51, v217, v51
	v_xor_b32_e32 v228, v50, v228
	v_cndmask_b32_e32 v228, 0, v228, vcc
	v_cmp_le_i32_e32 vcc, v226, v223
	v_or_b32_e32 v52, v217, v52
	v_xor_b32_e32 v229, v51, v229
	v_cndmask_b32_e32 v229, 0, v229, vcc
	v_cmp_le_i32_e32 vcc, v226, v224
	v_or_b32_e32 v53, v217, v53
	v_xor_b32_e32 v230, v52, v230
	v_cndmask_b32_e32 v230, 0, v230, vcc
	v_cmp_le_i32_e32 vcc, v226, v225
	v_xor_b32_e32 v231, v53, v231
	v_add_u32_e32 v0, 0xffff0000, v227
	v_cndmask_b32_e32 v231, 0, v231, vcc
	ds_write2st64_b32 v0, v228, v229 offset1:128
	ds_write2st64_b32 v227, v230, v231 offset1:128
	s_mov_b64 s[4:5], 0x8000
	v_lshl_add_u64 v[210:211], v[210:211], 0, s[4:5]
	v_add_u32_e32 v226, 0x100, v226
	v_add_u32_e32 v227, 0x400, v227
	s_and_b64 vcc, exec, s[2:3]
	s_cbranch_vccnz .LBB0_335
.LBB0_333:
	s_waitcnt vmcnt(3)
	v_mfma_f32_32x32x16_bf16 v[50:65], v[84:87], v[148:151], 0
	s_add_i32 s1, s1, 8
	s_cmp_gt_i32 s1, s34
	s_cselect_b64 s[2:3], -1, 0
	s_and_b64 vcc, exec, s[2:3]
	v_mfma_f32_32x32x16_bf16 v[34:49], v[100:103], v[148:151], 0
	v_mfma_f32_32x32x16_bf16 v[18:33], v[116:119], v[148:151], 0
	v_mfma_f32_32x32x16_bf16 v[2:17], v[132:135], v[148:151], 0
	global_load_dwordx4 v[148:151], v[210:211], off offset:-2048
	s_waitcnt vmcnt(3)
	v_mfma_f32_32x32x16_bf16 v[50:65], v[88:91], v[152:155], v[50:65]
	v_mfma_f32_32x32x16_bf16 v[34:49], v[104:107], v[152:155], v[34:49]
	v_mfma_f32_32x32x16_bf16 v[18:33], v[120:123], v[152:155], v[18:33]
	v_mfma_f32_32x32x16_bf16 v[2:17], v[136:139], v[152:155], v[2:17]
	global_load_dwordx4 v[152:155], v[210:211], off offset:-1024
	s_waitcnt vmcnt(3)
	v_mfma_f32_32x32x16_bf16 v[50:65], v[92:95], v[156:159], v[50:65]
	v_mfma_f32_32x32x16_bf16 v[34:49], v[108:111], v[156:159], v[34:49]
	v_mfma_f32_32x32x16_bf16 v[18:33], v[124:127], v[156:159], v[18:33]
	v_mfma_f32_32x32x16_bf16 v[2:17], v[140:143], v[156:159], v[2:17]
	global_load_dwordx4 v[156:159], v[210:211], off
	s_waitcnt vmcnt(3)
	v_mfma_f32_32x32x16_bf16 v[50:65], v[96:99], v[160:163], v[50:65]
	v_mfma_f32_32x32x16_bf16 v[34:49], v[112:115], v[160:163], v[34:49]
	v_mfma_f32_32x32x16_bf16 v[18:33], v[128:131], v[160:163], v[18:33]
	v_mfma_f32_32x32x16_bf16 v[2:17], v[144:147], v[160:163], v[2:17]
	global_load_dwordx4 v[160:163], v[210:211], off offset:1024
	s_branch .LBB0_332
.LBB0_335:
	s_add_i32 s29, s0, s29
	s_lshl_b32 s0, s0, 14
	s_ashr_i32 s14, s29, 6
	s_add_i32 s34, s0, 0
	s_cmp_gt_i32 s14, -1
	s_cselect_b64 s[30:31], -1, 0
	s_waitcnt vmcnt(1)
	v_mov_b32_e32 v4, 0
	s_and_b64 vcc, exec, s[30:31]
	v_mov_b32_e32 v0, 0
	s_waitcnt vmcnt(0)
	v_mov_b32_e32 v6, 0
	v_mov_b32_e32 v5, 0
	v_mov_b32_e32 v8, 0
	v_mov_b32_e32 v7, 0
	v_mov_b32_e32 v10, 0
	v_mov_b32_e32 v9, 0
	s_waitcnt lgkmcnt(0)
	s_barrier
	s_add_i32 s98, s45, s69
	s_mov_b32 s101, -1
	s_cmpk_ge_u32 s98, 0x800
	s_cbranch_scc1 .Lipf_none
	s_mov_b32 s101, s98
	s_and_b32 s99, s98, 0xff
	s_xor_b32 s100, s99, 0x1ff
	s_bitcmp1_b32 s98, 8
	s_cselect_b32 s99, s100, s99
	s_lshl_b32 s99, s99, 3
	s_lshr_b32 s98, s98, 9
	s_lshl_b32 s98, s98, 12
	s_or_b32 s100, s99, s98
	v_lshrrev_b32_e32 v164, 5, v221
	v_or_b32_e32 v164, s99, v164
	v_lshlrev_b32_e32 v164, 5, v164
	v_and_b32_e32 v164, 0x120, v164
	s_lshl_b32 s99, s99, 8
	s_and_b32 s99, s99, 0xf000
	v_or_b32_e32 v164, s99, v164
	v_lshlrev_b32_e32 v164, 1, v164
	s_lshr_b32 vcc_lo, s100, 8
	s_mulk_i32 vcc_lo, 0x49
	s_lshl_b32 vcc_lo, vcc_lo, 17
	s_add_u32 vcc_lo, vcc_lo, 0x1bb00000
	v_add_u32_e32 v164, vcc_lo, v164
	v_mov_b32_e32 v165, 0
	v_readlane_b32 s98, v237, 5
	v_readlane_b32 s99, v237, 6
	s_nop 3
	v_lshl_add_u64 v[166:167], s[98:99], 0, v[164:165]
	global_load_dwordx4 v[178:181], v[166:167], off offset:2048
	global_load_dwordx4 v[182:185], v[166:167], off offset:2064
	global_load_dwordx4 v[186:189], v[166:167], off offset:2176
	global_load_dwordx4 v[190:193], v[166:167], off offset:2192
	global_load_dwordx4 v[194:197], v[166:167], off offset:2304
	global_load_dwordx4 v[198:201], v[166:167], off offset:2320
	global_load_dwordx4 v[202:205], v[166:167], off offset:2432
	global_load_dwordx4 v[206:209], v[166:167], off offset:2448
	v_lshlrev_b32_e32 v168, 4, v221
	s_lshl_b32 vcc_lo, s100, 11
	s_add_u32 vcc_lo, vcc_lo, 0x1000
	v_add_u32_e32 v164, vcc_lo, v168
	v_lshl_add_u64 v[166:167], s[82:83], 0, v[164:165]
	s_mov_b64 vcc, 0x2000
	v_lshl_add_u64 v[170:171], v[166:167], 0, vcc
	global_load_dwordx4 v[84:87], v[166:167], off offset:-4096
	global_load_dwordx4 v[88:91], v[166:167], off offset:-3072
	global_load_dwordx4 v[92:95], v[166:167], off offset:-2048
	global_load_dwordx4 v[96:99], v[166:167], off offset:-1024
	global_load_dwordx4 v[100:103], v[166:167], off
	global_load_dwordx4 v[104:107], v[166:167], off offset:1024
	global_load_dwordx4 v[108:111], v[166:167], off offset:2048
	global_load_dwordx4 v[112:115], v[166:167], off offset:3072
	global_load_dwordx4 v[116:119], v[170:171], off offset:-4096
	global_load_dwordx4 v[120:123], v[170:171], off offset:-3072
	global_load_dwordx4 v[124:127], v[170:171], off offset:-2048
	global_load_dwordx4 v[128:131], v[170:171], off offset:-1024
	global_load_dwordx4 v[132:135], v[170:171], off
	global_load_dwordx4 v[136:139], v[170:171], off offset:1024
	global_load_dwordx4 v[140:143], v[170:171], off offset:2048
	global_load_dwordx4 v[144:147], v[170:171], off offset:3072
	v_readfirstlane_b32 vcc_lo, v212
	s_lshr_b32 vcc_lo, vcc_lo, 6
	s_lshl_b32 vcc_lo, vcc_lo, 12
	s_and_b32 s100, s100, 0xfffff000
	s_lshl_b32 s100, s100, 7
	s_add_u32 vcc_lo, vcc_lo, s100
	v_add_u32_e32 v164, vcc_lo, v168
	v_readlane_b32 s98, v239, 12
	v_readlane_b32 s99, v239, 13
	s_nop 3
	v_lshl_add_u64 v[166:167], s[98:99], 0, v[164:165]
	global_load_dwordx4 v[148:151], v[166:167], off
	global_load_dwordx4 v[152:155], v[166:167], off offset:1024
	global_load_dwordx4 v[156:159], v[166:167], off offset:2048
	global_load_dwordx4 v[160:163], v[166:167], off offset:3072
.Lipf_none:
	s_and_b64 vcc, exec, s[30:31]
	s_cbranch_vccz .LBB0_353
	v_cmp_ge_i32_e32 vcc, s29, v221
	v_mov_b32_e32 v0, 0
	v_mov_b32_e32 v4, 0
	s_and_saveexec_b64 s[0:1], vcc
	v_lshl_add_u32 v2, v221, 2, s34
	ds_read_b32 v4, v2
	s_or_b64 exec, exec, s[0:1]
	v_or_b32_e32 v2, 64, v221
	v_cmp_ge_i32_e32 vcc, s29, v2
	s_and_saveexec_b64 s[0:1], vcc
	v_lshl_add_u32 v0, v221, 2, s34
	ds_read_b32 v0, v0 offset:256
	s_or_b64 exec, exec, s[0:1]
	v_or_b32_e32 v2, 0x80, v221
	v_cmp_ge_i32_e32 vcc, s29, v2
	v_mov_b32_e32 v5, 0
	v_mov_b32_e32 v6, 0
	s_and_saveexec_b64 s[0:1], vcc
	v_lshl_add_u32 v2, v221, 2, s34
	ds_read_b32 v6, v2 offset:512
	s_or_b64 exec, exec, s[0:1]
	v_or_b32_e32 v2, 0xc0, v221
	v_cmp_ge_i32_e32 vcc, s29, v2
	s_and_saveexec_b64 s[0:1], vcc
	v_lshl_add_u32 v2, v221, 2, s34
	ds_read_b32 v5, v2 offset:768
	s_or_b64 exec, exec, s[0:1]
	v_or_b32_e32 v2, 0x100, v221
	v_cmp_ge_i32_e32 vcc, s29, v2
	v_mov_b32_e32 v7, 0
	v_mov_b32_e32 v8, 0
	s_and_saveexec_b64 s[0:1], vcc
	v_lshl_add_u32 v2, v221, 2, s34
	ds_read_b32 v8, v2 offset:1024
	s_or_b64 exec, exec, s[0:1]
	v_or_b32_e32 v2, 0x140, v221
	v_cmp_ge_i32_e32 vcc, s29, v2
	s_and_saveexec_b64 s[0:1], vcc
	v_lshl_add_u32 v2, v221, 2, s34
	ds_read_b32 v7, v2 offset:1280
	s_or_b64 exec, exec, s[0:1]
	v_or_b32_e32 v2, 0x180, v221
	v_cmp_ge_i32_e32 vcc, s29, v2
	v_mov_b32_e32 v9, 0
	v_mov_b32_e32 v10, 0
	s_and_saveexec_b64 s[0:1], vcc
	v_lshl_add_u32 v2, v221, 2, s34
	ds_read_b32 v10, v2 offset:1536
	s_or_b64 exec, exec, s[0:1]
	v_or_b32_e32 v2, 0x1c0, v221
	v_cmp_ge_i32_e32 vcc, s29, v2
	s_and_saveexec_b64 s[0:1], vcc
	v_lshl_add_u32 v2, v221, 2, s34
	ds_read_b32 v9, v2 offset:1792
	s_or_b64 exec, exec, s[0:1]
